# P6: lambda-parameter loads issued at phase entry so their latency overlaps the conv (prologue de-serialisation)
# speedup vs baseline: 1.0017x; 1.0017x over previous
.LBB0_547:
	s_cmp_lt_i32 s90, 7
	s_cselect_b64 s[2:3], -1, 0
	s_add_u32 s4, s94, 0x10400000
	s_addc_u32 s5, s95, 0
	s_and_b64 s[34:35], s[2:3], s[0:1]
	v_writelane_b32 v240, s4, 11
	s_andn2_b64 vcc, exec, s[34:35]
	s_nop 0
	v_writelane_b32 v240, s5, 12
	s_cbranch_vccnz .LBB0_624
	v_lshlrev_b32_e32 v243, 2, v147
	v_readlane_b32 s98, v241, 35
	v_readlane_b32 s99, v241, 36
	v_readlane_b32 s100, v241, 37
	v_readlane_b32 s101, v241, 38
	s_nop 4
	global_load_dword v244, v243, s[98:99]
	global_load_dword v245, v243, s[100:101]
	v_readlane_b32 s98, v241, 39
	v_readlane_b32 s99, v241, 40
	v_readlane_b32 s100, v241, 41
	v_readlane_b32 s101, v241, 42
	s_nop 4
	global_load_dword v246, v243, s[98:99]
	global_load_dword v247, v243, s[100:101]
	s_cmpk_lt_i32 s73, 0x100
	s_cbranch_scc1 .LBB0_550
	v_mbcnt_lo_u32_b32 v1, -1, 0
	v_mbcnt_hi_u32_b32 v196, -1, v1
	v_and_b32_e32 v1, 64, v196
	v_add_u32_e32 v1, 64, v1
	v_xor_b32_e32 v202, 1, v196
	v_xor_b32_e32 v201, 2, v196
	v_xor_b32_e32 v200, 4, v196
	v_xor_b32_e32 v199, 8, v196
	v_xor_b32_e32 v198, 16, v196
	v_xor_b32_e32 v197, 32, v196
	s_cbranch_execz .LBB0_551
	s_branch .LBB0_561

.LBB0_561:
	v_readlane_b32 s0, v241, 21
	v_readlane_b32 s48, v241, 37
	v_readlane_b32 s1, v241, 22
	v_readlane_b32 s2, v241, 23
	v_readlane_b32 s3, v241, 24
	v_readlane_b32 s4, v241, 25
	v_readlane_b32 s5, v241, 26
	v_readlane_b32 s6, v241, 27
	v_readlane_b32 s7, v241, 28
	v_readlane_b32 s49, v241, 38
	v_lshlrev_b32_e32 v128, 2, v147
	v_readlane_b32 s14, v241, 35
	v_readlane_b32 s15, v241, 36
	v_readlane_b32 s50, v241, 39
	v_readlane_b32 s51, v241, 40
	v_readlane_b32 s52, v241, 41
	v_readlane_b32 s53, v241, 42
	v_readlane_b32 s54, v241, 43
	v_readlane_b32 s55, v241, 44
	s_mov_b64 s[0:1], s[48:49]
	s_nop 0
	s_mov_b64 s[2:3], s[50:51]
	s_mov_b64 s[4:5], s[52:53]
	s_nop 0
	s_nop 0
	s_nop 0
	v_cmp_lt_i32_e32 vcc, v202, v1
	s_cmpk_gt_i32 s72, 0xff
	v_readlane_b32 s8, v241, 29
	v_cndmask_b32_e32 v6, v196, v202, vcc
	v_lshlrev_b32_e32 v154, 2, v6
	v_cmp_lt_i32_e32 vcc, v201, v1
	v_readlane_b32 s9, v241, 30
	v_readlane_b32 s10, v241, 31
	v_cndmask_b32_e32 v8, v196, v201, vcc
	v_lshlrev_b32_e32 v155, 2, v8
	v_cmp_lt_i32_e32 vcc, v200, v1
	v_readlane_b32 s11, v241, 32
	v_readlane_b32 s12, v241, 33
	v_readlane_b32 s13, v241, 34
	v_readlane_b32 s56, v241, 45
	v_readlane_b32 s57, v241, 46
	v_readlane_b32 s58, v241, 47
	v_readlane_b32 s59, v241, 48
	v_readlane_b32 s60, v241, 49
	v_readlane_b32 s61, v241, 50
	v_readlane_b32 s62, v241, 51
	v_readlane_b32 s63, v241, 52
	s_mov_b64 s[6:7], s[54:55]
	s_waitcnt vmcnt(0)
	v_mov_b32_e32 v2, v244
	v_mov_b32_e32 v3, v245
	v_mov_b32_e32 v4, v246
	v_mov_b32_e32 v5, v247
	v_mul_f32_e32 v6, v2, v3
	ds_bpermute_b32 v6, v154, v6
	v_mul_f32_e32 v7, v4, v5
	ds_bpermute_b32 v7, v154, v7
	s_waitcnt lgkmcnt(1)
	v_fmac_f32_e32 v6, v2, v3
	ds_bpermute_b32 v2, v155, v6
	s_waitcnt lgkmcnt(1)
	v_fmac_f32_e32 v7, v4, v5
	ds_bpermute_b32 v3, v155, v7
	v_cndmask_b32_e32 v4, v196, v200, vcc
	v_lshlrev_b32_e32 v156, 2, v4
	s_waitcnt lgkmcnt(1)
	v_add_f32_e32 v2, v6, v2
	ds_bpermute_b32 v4, v156, v2
	s_waitcnt lgkmcnt(1)
	v_add_f32_e32 v3, v7, v3
	ds_bpermute_b32 v5, v156, v3
	v_cmp_lt_i32_e32 vcc, v199, v1
	s_waitcnt lgkmcnt(1)
	v_add_f32_e32 v2, v2, v4
	v_cndmask_b32_e32 v6, v196, v199, vcc
	v_lshlrev_b32_e32 v157, 2, v6
	s_waitcnt lgkmcnt(0)
	v_add_f32_e32 v3, v3, v5
	ds_bpermute_b32 v4, v157, v2
	ds_bpermute_b32 v5, v157, v3
	v_cmp_lt_i32_e32 vcc, v198, v1
	s_waitcnt lgkmcnt(1)
	v_add_f32_e32 v2, v2, v4
	v_cndmask_b32_e32 v6, v196, v198, vcc
	v_lshlrev_b32_e32 v158, 2, v6
	s_waitcnt lgkmcnt(0)
	v_add_f32_e32 v3, v3, v5
	ds_bpermute_b32 v4, v158, v2
	ds_bpermute_b32 v5, v158, v3
	v_cmp_lt_i32_e32 vcc, v197, v1
	s_nop 1
	v_cndmask_b32_e32 v1, v196, v197, vcc
	v_lshlrev_b32_e32 v159, 2, v1
	s_waitcnt lgkmcnt(1)
	v_add_f32_e32 v1, v2, v4
	s_waitcnt lgkmcnt(0)
	v_add_f32_e32 v2, v3, v5
	ds_bpermute_b32 v3, v159, v1
	ds_bpermute_b32 v4, v159, v2
	s_cbranch_scc1 .LBB0_624
	v_writelane_b32 v240, s34, 13
	s_lshr_b32 s33, s21, 16
	s_and_b32 s0, s21, 0xffff
	v_writelane_b32 v240, s35, 14
	v_writelane_b32 v240, s86, 9
	s_waitcnt lgkmcnt(1)
	v_add_f32_e32 v1, v1, v3
	s_waitcnt lgkmcnt(0)
	v_add_f32_e32 v2, v2, v4
	s_add_u32 s28, s94, 0x4000
	v_writelane_b32 v240, s87, 10
	v_mul_f32_e32 v1, 0x3fb8aa3b, v1
	v_mul_f32_e32 v2, 0x3fb8aa3b, v2
	s_addc_u32 s29, s95, 0
	v_writelane_b32 v240, s96, 15
	v_exp_f32_e32 v1, v1
	v_exp_f32_e32 v2, v2
	s_add_u32 s1, s94, 0x1a400000
	v_writelane_b32 v240, s97, 16
	v_writelane_b32 v241, s1, 21
	s_addc_u32 s1, s95, 0
	v_writelane_b32 v240, s1, 17
	s_add_u32 s1, s94, 0x5000
	s_mov_b32 s2, 0x10400
	v_add_u32_e32 v3, 0x200, v146
	v_writelane_b32 v240, s1, 18
	s_addc_u32 s1, s95, 0
	s_addk_i32 s2, 0x100
	v_lshrrev_b32_e32 v163, 4, v3
	v_and_b32_e32 v6, 0x7f0, v3
	v_or_b32_e32 v3, 0x400, v146
	v_sub_f32_e32 v1, v1, v2
	v_mov_b32_e32 v2, s2
	s_movk_i32 s2, 0x7f0
	v_lshrrev_b32_e32 v164, 4, v3
	v_mov_b32_e32 v3, 0x400
	v_bitop3_b32 v7, v146, s2, v3 bitop3:0xc8
	s_bfe_u32 s2, s64, 0x10006
	v_add_u32_e32 v3, 0x600, v146
	v_lshrrev_b32_e32 v9, 5, v147
	s_lshl_b32 s4, s2, 3
	v_add_f32_e32 v160, 0x3e4ccccd, v1
	v_and_b32_e32 v1, 15, v146
	s_movk_i32 s3, 0x810
	v_lshrrev_b32_e32 v165, 4, v3
	v_and_b32_e32 v8, 0xff0, v3
	v_or_b32_e32 v3, s4, v9
	v_lshrrev_b32_e32 v12, 1, v146
	v_lshlrev_b32_e32 v13, 1, v146
	v_writelane_b32 v240, s1, 19
	s_lshr_b32 s1, s64, 7
	v_mad_u32_u24 v4, v1, s3, v2
	v_mad_u32_u24 v11, v3, s3, v2
	v_and_b32_e32 v2, 19, v146
	v_and_b32_e32 v12, 4, v12
	v_and_b32_e32 v13, 8, v13
	s_lshl_b32 s16, s1, 5
	s_lshr_b32 s17, s64, 8
	v_or3_b32 v2, v2, v12, v13
	v_writelane_b32 v240, s4, 20
	v_lshlrev_b32_e32 v2, 4, v2
	s_movk_i32 s4, 0x410
	s_cmpk_lt_u32 s64, 0x100
	v_mad_u32_u24 v166, v3, s4, v2
	v_lshrrev_b32_e32 v2, 4, v147
	v_lshrrev_b32_e32 v3, 3, v147
	s_cselect_b32 s4, 0x8200, 0
	v_lshlrev_b32_e32 v130, 4, v1
	v_lshl_or_b32 v2, s20, 3, v2
	v_lshl_or_b32 v169, s20, 4, v3
	v_mul_u32_u24_e32 v1, 0x410, v1
	s_addk_i32 s4, 0x100
	v_and_b32_e32 v12, 7, v146
	v_lshl_add_u32 v170, v2, 4, v1
	v_lshlrev_b32_e32 v1, 4, v169
	s_cmpk_gt_u32 s64, 0xff
	v_writelane_b32 v240, s4, 21
	s_cselect_b64 s[4:5], -1, 0
	v_mad_u32_u24 v172, v12, s3, v1
	v_bfe_u32 v1, v0, 10, 10
	v_bfe_u32 v0, v0, 20, 10
	s_mov_b32 s21, 0
	v_writelane_b32 v240, s4, 22
	s_lshl_b32 s68, s0, 8
	v_mad_u32_u24 v173, v0, s0, v1
	s_and_b32 s0, s64, 0xffffffc0
	v_writelane_b32 v240, s5, 23
	v_or_b32_e32 v0, s0, v147
	s_lshl_b64 s[4:5], s[20:21], 14
	s_and_b32 s0, 64, s64
	v_writelane_b32 v240, s4, 24
	s_cmp_eq_u32 s2, 0
	s_cselect_b64 s[2:3], -1, 0
	v_writelane_b32 v240, s5, 25
	v_writelane_b32 v240, s2, 26
	s_cmp_lg_u32 s0, 0
	v_mov_b32_e32 v131, 0
	v_writelane_b32 v240, s3, 27
	s_cselect_b64 s[2:3], -1, 0
	s_lshl_b32 s0, s1, 14
	v_mov_b32_e32 v3, v131
	v_writelane_b32 v240, s2, 28
	s_addk_i32 s0, 0x100
	v_lshlrev_b64 v[2:3], 11, v[2:3]
	v_writelane_b32 v240, s3, 29
	v_lshl_add_u32 v174, v147, 2, s0
	v_readlane_b32 s0, v241, 37
	v_and_b32_e32 v161, 31, v146
	v_lshl_add_u64 v[2:3], s[42:43], 0, v[2:3]
	v_writelane_b32 v240, s17, 30
	s_sub_i32 s0, 0, s17
	v_lshl_add_u64 v[132:133], s[66:67], 0, v[130:131]
	v_or_b32_e32 v10, s16, v161
	v_lshl_add_u64 v[134:135], v[2:3], 0, v[130:131]
	v_lshlrev_b32_e32 v130, 4, v12
	v_readlane_b32 s2, v241, 39
	v_readlane_b32 s3, v241, 40
	v_writelane_b32 v240, s0, 31
	s_mov_b32 s0, 0x20c30
	v_and_b32_e32 v5, 0x3f0, v146
	v_lshlrev_b32_e32 v10, 4, v10
	v_lshl_add_u64 v[136:137], s[40:41], 0, v[130:131]
	v_mul_i32_i24_e32 v171, -8, v9
	v_add_u32_e32 v138, 0x8000, v0
	v_add_u32_e32 v140, 0x8200, v0
	v_lshlrev_b32_e32 v0, 2, v9
	v_lshlrev_b32_e32 v130, 4, v9
	v_readlane_b32 s6, v241, 43
	v_readlane_b32 s7, v241, 44
	s_add_i32 s71, s0, 0x100
	s_mov_b32 s40, 0xc2000000
	s_mov_b32 s42, -2.0
	s_mov_b32 s44, 0xc2080000
	s_mov_b32 s46, -4.0
	s_mov_b32 s48, 0xc2100000
	s_mov_b32 s50, 0xc0c00000
	s_mov_b32 s52, 0xc2180000
	s_mov_b32 s54, 0xc1800000
	s_mov_b32 s56, 0xc2400000
	s_mov_b32 s58, 0xc1900000
	s_mov_b32 s60, 0xc2480000
	s_mov_b32 s62, 0xc1a00000
	s_mov_b32 s64, 0xc2500000
	s_mov_b32 s66, 0xc1b00000
	s_mov_b32 s82, 0xc2580000
	s_mov_b32 s84, 2.0
	s_mov_b32 s86, 4.0
	s_mov_b32 s0, s72
	s_mov_b32 s88, 0x40c00000
	s_mov_b32 s90, 0x41800000
	s_mov_b32 s92, 0x41900000
	s_mov_b32 s94, 0x41a00000
	s_mov_b32 s96, 0x41b00000
	s_mov_b32 s22, 0x42580000
	s_mov_b32 s74, 0x42500000
	s_mov_b32 s76, 0x42480000
	s_mov_b32 s24, 0x42400000
	s_mov_b32 s26, 0x42180000
	s_mov_b32 s72, 0x42100000
	s_mov_b32 s18, 0x42080000
	s_mov_b32 s34, 0x42000000
	v_cmp_eq_u32_e64 s[2:3], 0, v147
	v_lshrrev_b32_e32 v162, 4, v146
	v_mul_u32_u24_e32 v167, 0x810, v9
	v_lshlrev_b32_e32 v168, 4, v161
	v_ashrrev_i32_e32 v139, 31, v138
	v_ashrrev_i32_e32 v141, 31, v140
	v_lshl_add_u64 v[142:143], s[6:7], 0, v[130:131]
	v_add3_u32 v175, v171, s16, v161
	v_add_u32_e32 v176, v4, v5
	v_add_u32_e32 v177, v4, v6
	v_add_u32_e32 v178, v4, v7
	v_add_u32_e32 v179, v4, v8
	v_bfrev_b32_e32 v180, -2
	v_mov_b32_e32 v181, 0x260
	v_mov_b32_e32 v182, 0x3a83126f
	s_mov_b32 s41, 0xc2040000
	s_mov_b32 s43, 0xc0400000
	s_mov_b32 s45, 0xc20c0000
	s_mov_b32 s47, 0xc0a00000
	s_mov_b32 s49, 0xc2140000
	s_mov_b32 s51, 0xc0e00000
	s_mov_b32 s53, 0xc21c0000
	s_mov_b32 s55, 0xc1880000
	s_mov_b32 s57, 0xc2440000
	s_mov_b32 s59, 0xc1980000
	s_mov_b32 s61, 0xc24c0000
	s_mov_b32 s63, 0xc1a80000
	s_mov_b32 s65, 0xc2540000
	s_mov_b32 s67, 0xc1b80000
	s_mov_b32 s83, 0xc25c0000
	s_mov_b32 s85, 0x40400000
	s_mov_b32 s87, 0x40a00000
	s_mov_b32 s89, 0x40e00000
	s_mov_b32 s91, 0x41880000
	s_mov_b32 s93, 0x41980000
	s_mov_b32 s95, 0x41a80000
	s_mov_b32 s97, 0x41b80000
	s_mov_b32 s23, 0x425c0000
	s_mov_b32 s75, 0x42540000
	s_mov_b32 s77, 0x424c0000
	s_mov_b32 s25, 0x42440000
	s_mov_b32 s27, 0x421c0000
	s_mov_b32 s73, 0x42140000
	s_mov_b32 s19, 0x420c0000
	s_mov_b32 s35, 0x42040000
	v_mov_b32_e32 v183, 0x358637bd
	v_lshlrev_b32_e32 v144, 1, v0
	v_mov_b32_e32 v184, 1
	v_mov_b32_e32 v185, 0x9c
	v_add_u32_e32 v186, v11, v10
	v_writelane_b32 v240, s2, 32
	v_cmp_eq_u32_e64 s[6:7], 0, v196
	v_readlane_b32 s1, v241, 38
	v_readlane_b32 s4, v241, 41
	v_readlane_b32 s5, v241, 42
	v_readlane_b32 s8, v241, 45
	v_readlane_b32 s9, v241, 46
	v_readlane_b32 s10, v241, 47
	v_readlane_b32 s11, v241, 48
	v_readlane_b32 s12, v241, 49
	v_readlane_b32 s13, v241, 50
	v_readlane_b32 s14, v241, 51
	v_readlane_b32 s15, v241, 52
	v_writelane_b32 v241, s16, 37
	v_writelane_b32 v240, s3, 33
	s_branch .LBB0_564

	.amdhsa_kernel _Z10fwd_kernel4Args
		.amdhsa_group_segment_fixed_size 256
		.amdhsa_private_segment_fixed_size 0
		.amdhsa_kernarg_size 472
		.amdhsa_user_sgpr_count 2
		.amdhsa_user_sgpr_dispatch_ptr 0
		.amdhsa_user_sgpr_queue_ptr 0
		.amdhsa_user_sgpr_kernarg_segment_ptr 1
		.amdhsa_user_sgpr_dispatch_id 0
		.amdhsa_user_sgpr_kernarg_preload_length 0
		.amdhsa_user_sgpr_kernarg_preload_offset 0
		.amdhsa_user_sgpr_private_segment_size 0
		.amdhsa_uses_dynamic_stack 0
		.amdhsa_enable_private_segment 0
		.amdhsa_system_sgpr_workgroup_id_x 1
		.amdhsa_system_sgpr_workgroup_id_y 0
		.amdhsa_system_sgpr_workgroup_id_z 0
		.amdhsa_system_sgpr_workgroup_info 0
		.amdhsa_system_vgpr_workitem_id 2
		.amdhsa_next_free_vgpr 248
		.amdhsa_next_free_sgpr 102
		.amdhsa_accum_offset 248
		.amdhsa_reserve_vcc 1
		.amdhsa_float_round_mode_32 0
		.amdhsa_float_round_mode_16_64 0
		.amdhsa_float_denorm_mode_32 3
		.amdhsa_float_denorm_mode_16_64 3
		.amdhsa_dx10_clamp 1
		.amdhsa_ieee_mode 1
		.amdhsa_fp16_overflow 0
		.amdhsa_tg_split 0
		.amdhsa_exception_fp_ieee_invalid_op 0
		.amdhsa_exception_fp_denorm_src 0
		.amdhsa_exception_fp_ieee_div_zero 0
		.amdhsa_exception_fp_ieee_overflow 0
		.amdhsa_exception_fp_ieee_underflow 0
		.amdhsa_exception_fp_ieee_inexact 0
		.amdhsa_exception_int_div_zero 0
	.end_amdhsa_kernel

amdhsa.kernels:
  - .agpr_count:     0
    .args:
      - .offset:         0
        .size:           216
        .value_kind:     by_value
      - .offset:         216
        .size:           4
        .value_kind:     hidden_block_count_x
      - .offset:         220
        .size:           4
        .value_kind:     hidden_block_count_y
      - .offset:         224
        .size:           4
        .value_kind:     hidden_block_count_z
      - .offset:         228
        .size:           2
        .value_kind:     hidden_group_size_x
      - .offset:         230
        .size:           2
        .value_kind:     hidden_group_size_y
      - .offset:         232
        .size:           2
        .value_kind:     hidden_group_size_z
      - .offset:         234
        .size:           2
        .value_kind:     hidden_remainder_x
      - .offset:         236
        .size:           2
        .value_kind:     hidden_remainder_y
      - .offset:         238
        .size:           2
        .value_kind:     hidden_remainder_z
      - .offset:         256
        .size:           8
        .value_kind:     hidden_global_offset_x
      - .offset:         264
        .size:           8
        .value_kind:     hidden_global_offset_y
      - .offset:         272
        .size:           8
        .value_kind:     hidden_global_offset_z
      - .offset:         280
        .size:           2
        .value_kind:     hidden_grid_dims
      - .offset:         304
        .size:           8
        .value_kind:     hidden_multigrid_sync_arg
      - .offset:         336
        .size:           4
        .value_kind:     hidden_dynamic_lds_size
    .group_segment_fixed_size: 256
    .kernarg_segment_align: 8
    .kernarg_segment_size: 472
    .language:       OpenCL C
    .language_version:
      - 2
      - 0
    .max_flat_workgroup_size: 512
    .name:           _Z10fwd_kernel4Args
    .private_segment_fixed_size: 0
    .sgpr_count:     108
    .sgpr_spill_count: 103
    .symbol:         _Z10fwd_kernel4Args.kd
    .uniform_work_group_size: 1
    .uses_dynamic_stack: false
    .vgpr_count:     248
    .vgpr_spill_count: 0
    .wavefront_size: 64
